# GEMM phase prologues: second batch of first-tile LDS-DMA loads issued before the first counted wait (vmcnt 2->8)
# speedup vs baseline: 1.0015x; 1.0015x over previous
.LBB0_559:
	s_waitcnt vmcnt(0)
	v_bfe_u32 v18, v13, 4, 2
	v_readlane_b32 s34, v246, 12
	v_and_b32_e32 v1, 15, v13
	v_lshlrev_b32_e32 v19, 4, v18
	v_lshlrev_b32_e32 v13, 2, v13
	s_mov_b64 s[2:3], 0x80
	v_mov_b32_e32 v187, v3
	v_readlane_b32 s35, v246, 13
	s_and_b32 s7, s7, 3
	v_lshl_or_b32 v20, v1, 6, v19
	s_lshl_b32 s10, s14, 13
	v_and_b32_e32 v21, 32, v13
	s_add_i32 m0, s16, 0x18000
	v_lshl_add_u64 v[4:5], v[4:5], 0, s[2:3]
	v_lshl_add_u64 v[14:15], s[34:35], 0, v[186:187]
	v_mov_b32_e32 v183, v3
	v_bitop3_b32 v22, v20, s10, v21 bitop3:0xde
	s_lshl_b32 s10, s7, 12
	global_load_lds_dwordx4 v[4:5], off
	v_lshl_add_u64 v[4:5], v[6:7], 0, s[2:3]
	s_add_i32 m0, s16, 0x1a000
	s_add_i32 s20, s16, 0x8000
	s_add_i32 s21, s16, 0xa000
	v_lshl_add_u64 v[16:17], s[34:35], 0, v[182:183]
	v_bitop3_b32 v193, v20, s10, v21 bitop3:0xde
	global_load_lds_dwordx4 v[4:5], off
	v_lshl_add_u64 v[4:5], v[14:15], 0, s[2:3]
	s_mov_b32 m0, s20
	s_add_u32 s10, s8, 0x80080
	global_load_lds_dwordx4 v[4:5], off
	v_lshl_add_u64 v[4:5], v[16:17], 0, s[2:3]
	s_mov_b32 m0, s21
	s_addc_u32 s11, s9, 0
	global_load_lds_dwordx4 v[4:5], off
	s_add_i32 m0, s16, 0x1c000
	v_lshl_add_u64 v[4:5], s[10:11], 0, v[184:185]
	global_load_lds_dwordx4 v[4:5], off
	v_lshl_add_u64 v[4:5], s[10:11], 0, v[180:181]
	s_add_i32 m0, s16, 0x1e000
	s_cmpk_lt_u32 s6, 0x100
	global_load_lds_dwordx4 v[4:5], off
	v_lshlrev_b32_e32 v4, 15, v11
	v_and_b32_e32 v4, 0xffff0000, v4
	v_lshl_add_u32 v4, v10, 12, v4
	v_and_b32_e32 v5, 1, v11
	v_lshl_or_b32 v4, v5, 6, v4
	v_lshl_add_u32 v188, v12, 1, v4
	v_lshlrev_b32_e32 v4, 15, v2
	v_and_b32_e32 v4, 0xffff0000, v4
	s_waitcnt vmcnt(8)
	s_barrier
	s_waitcnt vmcnt(6)
	s_cselect_b64 s[46:47], -1, 0
	s_bitcmp0_b32 s6, 6
	v_lshl_add_u32 v4, v8, 12, v4
	v_and_b32_e32 v2, 1, v2
	v_lshl_or_b32 v194, s7, 6, v19
	s_cselect_b64 s[38:39], -1, 0
	s_lshl_b32 s6, s7, 3
	v_lshl_or_b32 v2, v2, 6, v4
	v_readlane_b32 s2, v246, 8
	v_lshl_or_b32 v192, s14, 6, v1
	v_cmp_lt_u32_e64 s[36:37], 1, v18
	s_mov_b32 s24, 0
	v_and_b32_e32 v195, 64, v13
	v_or_b32_e32 v196, 16, v1
	v_or_b32_e32 v197, 32, v1
	v_or_b32_e32 v198, 48, v1
	v_cmp_eq_u32_e64 s[40:41], 0, v18
	v_or_b32_e32 v199, 0xffffec00, v194
	s_or_b32 s25, s6, 0xffffff80
	v_mov_b32_e32 v189, v3
	v_lshl_add_u32 v190, v9, 1, v2
	v_mov_b32_e32 v191, v3
	v_add_u32_e32 v207, 0, v22
	v_readlane_b32 s26, v247, 48
	s_mov_b32 s27, s2
	s_mov_b64 s[6:7], s[34:35]
	s_barrier
	v_readlane_b32 s3, v246, 9
	s_branch .LBB0_562

.LBB0_1006:
	v_mov_b32_e32 v151, v3
	v_lshl_add_u64 v[10:11], s[18:19], 0, v[150:151]
	v_mov_b32_e32 v147, v3
	v_readlane_b32 s16, v247, 58
	v_and_b32_e32 v9, 15, v1
	v_and_b32_e32 v18, 48, v1
	v_lshlrev_b32_e32 v1, 2, v1
	s_mov_b64 s[2:3], 0x80
	v_lshl_add_u64 v[12:13], s[18:19], 0, v[146:147]
	v_mov_b32_e32 v153, v3
	v_readlane_b32 s17, v247, 59
	s_and_b32 s7, s7, 3
	s_lshl_b32 s9, s8, 13
	v_lshl_or_b32 v19, v9, 6, v18
	v_and_b32_e32 v1, 32, v1
	s_add_i32 m0, s34, 0x18000
	v_lshl_add_u64 v[10:11], v[10:11], 0, s[2:3]
	v_lshl_add_u64 v[14:15], s[16:17], 0, v[152:153]
	v_mov_b32_e32 v149, v3
	v_bitop3_b32 v20, v19, s9, v1 bitop3:0xde
	s_lshl_b32 s9, s7, 12
	global_load_lds_dwordx4 v[10:11], off
	v_lshl_add_u64 v[10:11], v[12:13], 0, s[2:3]
	s_add_i32 m0, s34, 0x1a000
	s_add_i32 s40, s34, 0x8000
	s_add_i32 s41, s34, 0xa000
	v_lshl_add_u64 v[16:17], s[16:17], 0, v[148:149]
	global_load_lds_dwordx4 v[10:11], off
	v_lshl_add_u64 v[10:11], v[14:15], 0, s[2:3]
	s_mov_b32 m0, s40
	s_add_u32 s10, s18, 0x80080
	global_load_lds_dwordx4 v[10:11], off
	v_lshl_add_u64 v[10:11], v[16:17], 0, s[2:3]
	s_mov_b32 m0, s41
	s_addc_u32 s11, s19, 0
	global_load_lds_dwordx4 v[10:11], off
	s_add_i32 m0, s34, 0x1c000
	v_lshl_add_u64 v[10:11], s[10:11], 0, v[150:151]
	global_load_lds_dwordx4 v[10:11], off
	v_lshl_add_u64 v[10:11], s[10:11], 0, v[146:147]
	s_add_i32 m0, s34, 0x1e000
	v_lshlrev_b32_e32 v9, 12, v9
	global_load_lds_dwordx4 v[10:11], off
	v_bitop3_b32 v1, v19, s9, v1 bitop3:0xde
	s_lshl_b32 s9, s7, 6
	v_lshl_or_b32 v9, s8, 18, v9
	v_or3_b32 v162, s9, v9, v18
	v_lshlrev_b32_e32 v9, 15, v7
	v_and_b32_e32 v9, 0xffff0000, v9
	v_lshl_add_u32 v6, v6, 12, v9
	v_and_b32_e32 v7, 1, v7
	v_lshl_or_b32 v6, v7, 6, v6
	v_lshl_add_u32 v154, v8, 1, v6
	v_lshlrev_b32_e32 v6, 15, v2
	v_and_b32_e32 v6, 0xffff0000, v6
	s_waitcnt vmcnt(8)
	s_barrier
	s_waitcnt vmcnt(6)
	v_lshl_add_u32 v4, v4, 12, v6
	v_and_b32_e32 v2, 1, v2
	s_cmpk_lt_u32 s6, 0x100
	v_lshl_or_b32 v2, v2, 6, v4
	v_readlane_b32 s2, v247, 54
	s_cselect_b64 s[6:7], -1, 0
	v_mov_b32_e32 v155, v3
	v_lshl_add_u32 v156, v5, 1, v2
	v_mov_b32_e32 v157, v3
	s_mov_b32 s42, 0
	v_add_u32_e32 v163, 0, v20
	v_readlane_b32 s20, v247, 53
	s_mov_b32 s21, s2
	s_barrier
	v_readlane_b32 s3, v247, 55
	s_branch .LBB0_1009

.LBB0_1077:
	v_lshrrev_b32_e32 v18, 1, v1
	v_and_b32_e32 v18, 24, v18
	v_mov_b32_e32 v137, v3
	v_and_b32_e32 v9, 15, v1
	v_lshlrev_b32_e32 v19, 1, v18
	v_lshlrev_b32_e32 v1, 2, v1
	v_lshl_add_u64 v[10:11], s[20:21], 0, v[136:137]
	v_mov_b32_e32 v133, v3
	v_readlane_b32 s18, v246, 21
	v_lshl_or_b32 v19, v9, 6, v19
	s_lshl_b32 s9, s8, 13
	v_and_b32_e32 v1, 32, v1
	s_lshl_b32 s7, s7, 5
	s_mov_b64 s[2:3], 0x80
	v_lshl_add_u64 v[12:13], s[20:21], 0, v[132:133]
	v_mov_b32_e32 v139, v3
	v_readlane_b32 s19, v246, 22
	v_bitop3_b32 v20, v19, s9, v1 bitop3:0xde
	s_and_b32 s9, s7, 0x60
	s_add_i32 m0, s34, 0x18000
	v_lshl_add_u64 v[10:11], v[10:11], 0, s[2:3]
	v_lshl_add_u64 v[14:15], s[18:19], 0, v[138:139]
	v_mov_b32_e32 v135, v3
	s_lshl_b32 s7, s9, 7
	global_load_lds_dwordx4 v[10:11], off
	v_lshl_add_u64 v[10:11], v[12:13], 0, s[2:3]
	s_add_i32 m0, s34, 0x1a000
	s_add_i32 s42, s34, 0x8000
	s_add_i32 s43, s34, 0xa000
	v_lshl_add_u64 v[16:17], s[18:19], 0, v[134:135]
	global_load_lds_dwordx4 v[10:11], off
	v_lshl_add_u64 v[10:11], v[14:15], 0, s[2:3]
	s_mov_b32 m0, s42
	s_add_u32 s10, s20, 0x80080
	global_load_lds_dwordx4 v[10:11], off
	v_lshl_add_u64 v[10:11], v[16:17], 0, s[2:3]
	s_mov_b32 m0, s43
	s_addc_u32 s11, s21, 0
	global_load_lds_dwordx4 v[10:11], off
	s_add_i32 m0, s34, 0x1c000
	v_lshl_add_u64 v[10:11], s[10:11], 0, v[136:137]
	global_load_lds_dwordx4 v[10:11], off
	v_lshl_add_u64 v[10:11], s[10:11], 0, v[132:133]
	s_add_i32 m0, s34, 0x1e000
	v_lshlrev_b32_e32 v9, 11, v9
	global_load_lds_dwordx4 v[10:11], off
	v_lshl_or_b32 v9, s8, 17, v9
	v_or3_b32 v9, v18, v9, s9
	v_lshlrev_b32_e32 v144, 1, v9
	v_lshlrev_b32_e32 v9, 15, v7
	v_and_b32_e32 v9, 0xffff0000, v9
	v_lshl_add_u32 v6, v6, 12, v9
	v_and_b32_e32 v7, 1, v7
	v_lshl_or_b32 v6, v7, 6, v6
	v_lshl_add_u32 v140, v8, 1, v6
	v_lshlrev_b32_e32 v6, 15, v2
	v_and_b32_e32 v6, 0xffff0000, v6
	s_waitcnt vmcnt(8)
	s_barrier
	s_waitcnt vmcnt(6)
	v_lshl_add_u32 v4, v4, 12, v6
	v_and_b32_e32 v2, 1, v2
	s_cmpk_lt_u32 s6, 0x100
	v_lshl_or_b32 v2, v2, 6, v4
	v_readlane_b32 s2, v246, 25
	s_mov_b32 s47, 32
	v_bitop3_b32 v1, v19, s7, v1 bitop3:0xde
	s_cselect_b64 s[6:7], -1, 0
	v_mov_b32_e32 v141, v3
	v_lshl_add_u32 v142, v5, 1, v2
	v_mov_b32_e32 v143, v3
	s_mov_b32 s50, 0
	v_add_u32_e32 v145, 0, v20
	s_mov_b32 s48, s2
	v_readlane_b32 s49, v246, 16
	s_mov_b32 s10, 0
	s_barrier
	v_readlane_b32 s3, v246, 26
	s_branch .LBB0_1080

.LBB0_1216:
	v_lshrrev_b32_e32 v20, 1, v10
	v_and_b32_e32 v20, 24, v20
	s_lshl_b32 s9, s9, 5
	v_and_b32_e32 v11, 15, v10
	v_lshlrev_b32_e32 v21, 1, v20
	v_lshlrev_b32_e32 v10, 2, v10
	s_and_b32 s12, s9, 0x60
	v_lshl_add_u64 v[12:13], s[20:21], 0, v[2:3]
	v_mov_b32_e32 v133, v3
	v_readlane_b32 s18, v246, 4
	v_lshl_or_b32 v1, s10, 6, v11
	v_lshl_or_b32 v11, v11, 6, v21
	s_lshl_b32 s10, s10, 13
	v_and_b32_e32 v10, 32, v10
	s_lshl_b32 s9, s12, 7
	s_mov_b64 s[2:3], 0x80
	v_lshl_add_u64 v[14:15], s[20:21], 0, v[132:133]
	v_mov_b32_e32 v137, v3
	v_readlane_b32 s19, v246, 5
	v_bitop3_b32 v21, v11, s10, v10 bitop3:0xde
	v_bitop3_b32 v144, v11, s9, v10 bitop3:0xde
	s_add_i32 m0, s34, 0x18000
	v_lshl_add_u64 v[10:11], v[12:13], 0, s[2:3]
	v_lshl_add_u64 v[16:17], s[18:19], 0, v[136:137]
	v_mov_b32_e32 v135, v3
	global_load_lds_dwordx4 v[10:11], off
	v_lshl_add_u64 v[10:11], v[14:15], 0, s[2:3]
	s_add_i32 m0, s34, 0x1a000
	s_add_i32 s44, s34, 0x8000
	s_add_i32 s45, s34, 0xa000
	v_lshl_add_u64 v[18:19], s[18:19], 0, v[134:135]
	global_load_lds_dwordx4 v[10:11], off
	v_lshl_add_u64 v[10:11], v[16:17], 0, s[2:3]
	s_mov_b32 m0, s44
	s_add_u32 s10, s20, 0x80080
	global_load_lds_dwordx4 v[10:11], off
	v_lshl_add_u64 v[10:11], v[18:19], 0, s[2:3]
	s_mov_b32 m0, s45
	s_addc_u32 s11, s21, 0
	global_load_lds_dwordx4 v[10:11], off
	s_add_i32 m0, s34, 0x1c000
	v_lshl_add_u64 v[10:11], s[10:11], 0, v[2:3]
	global_load_lds_dwordx4 v[10:11], off
	v_lshl_add_u64 v[10:11], s[10:11], 0, v[132:133]
	s_add_i32 m0, s34, 0x1e000
	s_cmpk_lt_u32 s8, 0x100
	global_load_lds_dwordx4 v[10:11], off
	v_lshlrev_b32_e32 v10, 15, v8
	v_and_b32_e32 v10, 0xffff0000, v10
	v_lshl_add_u32 v7, v7, 12, v10
	v_and_b32_e32 v8, 1, v8
	v_lshl_or_b32 v7, v8, 6, v7
	v_lshl_add_u32 v138, v9, 1, v7
	v_lshlrev_b32_e32 v7, 15, v4
	v_and_b32_e32 v7, 0xffff0000, v7
	s_waitcnt vmcnt(8)
	s_barrier
	s_waitcnt vmcnt(6)
	v_lshl_add_u32 v5, v5, 12, v7
	v_and_b32_e32 v4, 1, v4
	v_lshl_or_b32 v4, v4, 6, v5
	v_readlane_b32 s2, v246, 0
	s_cselect_b64 s[8:9], -1, 0
	v_or_b32_e32 v145, s12, v20
	v_mov_b32_e32 v139, v3
	v_lshl_add_u32 v140, v6, 1, v4
	v_mov_b32_e32 v141, v3
	s_mov_b32 s46, 0
	v_add_u32_e32 v146, 0, v21
	v_readlane_b32 s47, v247, 63
	s_mov_b32 s48, s2
	s_barrier
	v_readlane_b32 s3, v246, 1
	s_branch .LBB0_1219

.LBB0_1285:
	v_lshrrev_b32_e32 v18, 1, v1
	v_and_b32_e32 v18, 24, v18
	v_and_b32_e32 v13, 15, v1
	v_lshlrev_b32_e32 v19, 1, v18
	v_lshlrev_b32_e32 v1, 2, v1
	v_readlane_b32 s20, v246, 31
	v_lshl_or_b32 v19, v13, 6, v19
	s_lshl_b32 s11, s10, 13
	v_and_b32_e32 v1, 32, v1
	s_lshl_b32 s9, s9, 5
	s_mov_b64 s[2:3], 0x80
	v_mov_b32_e32 v139, v3
	v_readlane_b32 s21, v246, 32
	v_bitop3_b32 v20, v19, s11, v1 bitop3:0xde
	s_and_b32 s11, s9, 0x60
	s_add_i32 m0, s40, 0x18000
	v_lshl_add_u64 v[4:5], v[4:5], 0, s[2:3]
	v_lshl_add_u64 v[14:15], s[20:21], 0, v[138:139]
	v_mov_b32_e32 v135, v3
	s_lshl_b32 s9, s11, 7
	global_load_lds_dwordx4 v[4:5], off
	v_lshl_add_u64 v[4:5], v[6:7], 0, s[2:3]
	s_add_i32 m0, s40, 0x1a000
	s_add_i32 s44, s40, 0x8000
	s_add_i32 s45, s40, 0xa000
	v_lshl_add_u64 v[16:17], s[20:21], 0, v[134:135]
	global_load_lds_dwordx4 v[4:5], off
	v_lshl_add_u64 v[4:5], v[14:15], 0, s[2:3]
	s_mov_b32 m0, s44
	s_add_u32 s12, s24, 0x200080
	global_load_lds_dwordx4 v[4:5], off
	v_lshl_add_u64 v[4:5], v[16:17], 0, s[2:3]
	s_mov_b32 m0, s45
	s_addc_u32 s13, s25, 0
	global_load_lds_dwordx4 v[4:5], off
	s_add_i32 m0, s40, 0x1c000
	v_lshl_add_u64 v[4:5], s[12:13], 0, v[136:137]
	global_load_lds_dwordx4 v[4:5], off
	v_lshl_add_u64 v[4:5], s[12:13], 0, v[132:133]
	s_add_i32 m0, s40, 0x1e000
	s_cmpk_lt_u32 s8, 0x100
	global_load_lds_dwordx4 v[4:5], off
	v_lshlrev_b32_e32 v4, 11, v13
	v_lshl_or_b32 v4, s10, 17, v4
	v_or3_b32 v4, v18, v4, s11
	v_lshlrev_b32_e32 v144, 1, v4
	v_lshlrev_b32_e32 v4, 17, v11
	v_and_b32_e32 v4, 0xfffc0000, v4
	v_lshl_add_u32 v4, v10, 14, v4
	v_and_b32_e32 v5, 1, v11
	v_lshl_or_b32 v4, v5, 6, v4
	v_lshl_add_u32 v140, v12, 1, v4
	v_lshlrev_b32_e32 v4, 17, v2
	v_and_b32_e32 v4, 0xfffc0000, v4
	s_waitcnt vmcnt(8)
	s_barrier
	s_waitcnt vmcnt(6)
	v_lshl_add_u32 v4, v8, 14, v4
	v_and_b32_e32 v2, 1, v2
	v_lshl_or_b32 v2, v2, 6, v4
	v_readlane_b32 s2, v246, 25
	v_bitop3_b32 v1, v19, s9, v1 bitop3:0xde
	s_cselect_b64 s[8:9], -1, 0
	v_mov_b32_e32 v141, v3
	v_lshl_add_u32 v142, v9, 1, v2
	v_mov_b32_e32 v143, v3
	s_movk_i32 s51, 0x80
	s_mov_b32 s52, 0
	v_add_u32_e32 v145, 0, v20
	s_mov_b32 s49, s2
	v_readlane_b32 s50, v246, 16
	s_mov_b32 s12, 0
	s_barrier
	v_readlane_b32 s3, v246, 26
	s_branch .LBB0_1288
